# phase-0 adaLN GEMV: rolling window of 48 row loads in flight (one new load per consumed row) instead of load-32 / wait-all / consume
# baseline (speedup 1.0000x reference)
; DI float silu(float x) { return x * __builtin_amdgcn_rcpf(1.f + __expf(-x)); }
; DI int tid() { int t = threadIdx.x & 255; asm volatile("" : "+v"(t)); return t; }
; DI void adaln_item(const Params& p, int it, char* smem) {
;   const int l = it / 192, n0 = (it % 192) * 64;
;   float* sc = (float*)smem;
;   float* sx = sc + 2048;
;   float* red = sx + 2048;
;   const int t = tid();
;   __syncthreads();
;   for (int k = t; k < 2048; k += 256) { sc[k] = silu(p.c[k]); sx[k] = silu(p.c_ctx[k]); }
;   __syncthreads();
;   const int col = t & 63, kq = t >> 6;
;   const float* wp = p.w_ada + (size_t)l * 2048 * 12288 + (size_t)(kq * 512) * 12288 + n0 + col;
;   float a0 = 0.f, a1 = 0.f;
;   for (int k = 0; k < 512; k += 32) {
;     float wv[32];
; #pragma unroll
;     for (int e = 0; e < 32; ++e) wv[e] = __builtin_nontemporal_load(wp + (size_t)(k + e) * 12288);
.LBB0_65:
	s_or_b64 exec, exec, s[0:1]
	s_mul_hi_i32 s0, s13, 0x2aaaaaab
	s_lshr_b32 s1, s0, 31
	s_ashr_i32 s6, s0, 5
	s_add_i32 s6, s6, s1
	s_mul_i32 s0, s6, 0xc0
	s_sub_i32 s0, s13, s0
	s_lshl_b32 s4, s0, 6
	s_mul_i32 s0, s6, 0x6000000
	s_mul_hi_i32 s1, s6, 0x6000000
	s_add_u32 s0, s76, s0
	v_ashrrev_i32_e32 v43, 6, v42
	s_addc_u32 s1, s77, s1
	v_lshlrev_b32_e32 v4, 9, v43
	v_mov_b64_e32 v[2:3], s[0:1]
	s_mov_b32 s0, 0xc000
	v_and_b32_e32 v44, 63, v42
	v_mad_i64_i32 v[2:3], s[0:1], v4, s0, v[2:3]
	s_ashr_i32 s5, s4, 31
	v_lshl_add_u64 v[2:3], s[4:5], 2, v[2:3]
	v_lshlrev_b32_e32 v180, 2, v44
	v_mov_b32_e32 v48, 0
	v_lshl_add_u64 v[46:47], v[2:3], 0, v[180:181]
	v_lshl_add_u32 v45, v43, 11, s3
	s_movk_i32 s7, 0xffe0
	v_mov_b32_e32 v49, v48
	s_waitcnt lgkmcnt(0)
	s_barrier
	v_lshlrev_b32_e32 v162, 2, v44
	s_nop 0
	v_readfirstlane_b32 s0, v46
	v_readfirstlane_b32 s1, v47
	s_nop 4
	global_load_dword v66, v162, s[0:1] nt
	s_add_u32 s0, s0, 0xc000
	s_addc_u32 s1, s1, 0
	global_load_dword v67, v162, s[0:1] nt
	s_add_u32 s0, s0, 0xc000
	s_addc_u32 s1, s1, 0
	global_load_dword v68, v162, s[0:1] nt
	s_add_u32 s0, s0, 0xc000
	s_addc_u32 s1, s1, 0
	global_load_dword v69, v162, s[0:1] nt
	s_add_u32 s0, s0, 0xc000
	s_addc_u32 s1, s1, 0
	global_load_dword v70, v162, s[0:1] nt
	s_add_u32 s0, s0, 0xc000
	s_addc_u32 s1, s1, 0
	global_load_dword v71, v162, s[0:1] nt
	s_add_u32 s0, s0, 0xc000
	s_addc_u32 s1, s1, 0
	global_load_dword v72, v162, s[0:1] nt
	s_add_u32 s0, s0, 0xc000
	s_addc_u32 s1, s1, 0
	global_load_dword v73, v162, s[0:1] nt
	s_add_u32 s0, s0, 0xc000
	s_addc_u32 s1, s1, 0
	global_load_dword v74, v162, s[0:1] nt
	s_add_u32 s0, s0, 0xc000
	s_addc_u32 s1, s1, 0
	global_load_dword v75, v162, s[0:1] nt
	s_add_u32 s0, s0, 0xc000
	s_addc_u32 s1, s1, 0
	global_load_dword v76, v162, s[0:1] nt
	s_add_u32 s0, s0, 0xc000
	s_addc_u32 s1, s1, 0
	global_load_dword v77, v162, s[0:1] nt
	s_add_u32 s0, s0, 0xc000
	s_addc_u32 s1, s1, 0
	global_load_dword v78, v162, s[0:1] nt
	s_add_u32 s0, s0, 0xc000
	s_addc_u32 s1, s1, 0
	global_load_dword v79, v162, s[0:1] nt
	s_add_u32 s0, s0, 0xc000
	s_addc_u32 s1, s1, 0
	global_load_dword v80, v162, s[0:1] nt
	s_add_u32 s0, s0, 0xc000
	s_addc_u32 s1, s1, 0
	global_load_dword v81, v162, s[0:1] nt
	s_add_u32 s0, s0, 0xc000
	s_addc_u32 s1, s1, 0
	global_load_dword v82, v162, s[0:1] nt
	s_add_u32 s0, s0, 0xc000
	s_addc_u32 s1, s1, 0
	global_load_dword v83, v162, s[0:1] nt
	s_add_u32 s0, s0, 0xc000
	s_addc_u32 s1, s1, 0
	global_load_dword v84, v162, s[0:1] nt
	s_add_u32 s0, s0, 0xc000
	s_addc_u32 s1, s1, 0
	global_load_dword v85, v162, s[0:1] nt
	s_add_u32 s0, s0, 0xc000
	s_addc_u32 s1, s1, 0
	global_load_dword v86, v162, s[0:1] nt
	s_add_u32 s0, s0, 0xc000
	s_addc_u32 s1, s1, 0
	global_load_dword v87, v162, s[0:1] nt
	s_add_u32 s0, s0, 0xc000
	s_addc_u32 s1, s1, 0
	global_load_dword v88, v162, s[0:1] nt
	s_add_u32 s0, s0, 0xc000
	s_addc_u32 s1, s1, 0
	global_load_dword v89, v162, s[0:1] nt
	s_add_u32 s0, s0, 0xc000
	s_addc_u32 s1, s1, 0
	global_load_dword v90, v162, s[0:1] nt
	s_add_u32 s0, s0, 0xc000
	s_addc_u32 s1, s1, 0
	global_load_dword v91, v162, s[0:1] nt
	s_add_u32 s0, s0, 0xc000
	s_addc_u32 s1, s1, 0
	global_load_dword v92, v162, s[0:1] nt
	s_add_u32 s0, s0, 0xc000
	s_addc_u32 s1, s1, 0
	global_load_dword v93, v162, s[0:1] nt
	s_add_u32 s0, s0, 0xc000
	s_addc_u32 s1, s1, 0
	global_load_dword v94, v162, s[0:1] nt
	s_add_u32 s0, s0, 0xc000
	s_addc_u32 s1, s1, 0
	global_load_dword v95, v162, s[0:1] nt
	s_add_u32 s0, s0, 0xc000
	s_addc_u32 s1, s1, 0
	global_load_dword v96, v162, s[0:1] nt
	s_add_u32 s0, s0, 0xc000
	s_addc_u32 s1, s1, 0
	global_load_dword v97, v162, s[0:1] nt
	s_add_u32 s0, s0, 0xc000
	s_addc_u32 s1, s1, 0
	global_load_dword v98, v162, s[0:1] nt
	s_add_u32 s0, s0, 0xc000
	s_addc_u32 s1, s1, 0
	global_load_dword v99, v162, s[0:1] nt
	s_add_u32 s0, s0, 0xc000
	s_addc_u32 s1, s1, 0
	global_load_dword v100, v162, s[0:1] nt
	s_add_u32 s0, s0, 0xc000
	s_addc_u32 s1, s1, 0
	global_load_dword v101, v162, s[0:1] nt
	s_add_u32 s0, s0, 0xc000
	s_addc_u32 s1, s1, 0
	global_load_dword v102, v162, s[0:1] nt
	s_add_u32 s0, s0, 0xc000
	s_addc_u32 s1, s1, 0
	global_load_dword v103, v162, s[0:1] nt
	s_add_u32 s0, s0, 0xc000
	s_addc_u32 s1, s1, 0
	global_load_dword v104, v162, s[0:1] nt
	s_add_u32 s0, s0, 0xc000
	s_addc_u32 s1, s1, 0
	global_load_dword v105, v162, s[0:1] nt
	s_add_u32 s0, s0, 0xc000
	s_addc_u32 s1, s1, 0
	global_load_dword v106, v162, s[0:1] nt
	s_add_u32 s0, s0, 0xc000
	s_addc_u32 s1, s1, 0
	global_load_dword v107, v162, s[0:1] nt
	s_add_u32 s0, s0, 0xc000
	s_addc_u32 s1, s1, 0
	global_load_dword v108, v162, s[0:1] nt
	s_add_u32 s0, s0, 0xc000
	s_addc_u32 s1, s1, 0
	global_load_dword v109, v162, s[0:1] nt
	s_add_u32 s0, s0, 0xc000
	s_addc_u32 s1, s1, 0
	global_load_dword v110, v162, s[0:1] nt
	s_add_u32 s0, s0, 0xc000
	s_addc_u32 s1, s1, 0
	global_load_dword v111, v162, s[0:1] nt
	s_add_u32 s0, s0, 0xc000
	s_addc_u32 s1, s1, 0
	global_load_dword v112, v162, s[0:1] nt
	s_add_u32 s0, s0, 0xc000
	s_addc_u32 s1, s1, 0
	global_load_dword v113, v162, s[0:1] nt
	ds_read_b128 v[114:117], v45 offset:0
	ds_read_b128 v[118:121], v45 offset:16
	ds_read_b128 v[122:125], v45 offset:32
	ds_read_b128 v[126:129], v45 offset:48
	ds_read_b128 v[194:197], v45 offset:8192
	ds_read_b128 v[198:201], v45 offset:8208
	ds_read_b128 v[202:205], v45 offset:8224
	ds_read_b128 v[206:209], v45 offset:8240
	s_mov_b32 s7, 0
; DI void adaln_item(const Params& p, int it, char* smem) {
;     ...
;   for (int k = 0; k < 512; k += 32) {
;     float wv[32];
; #pragma unroll
;     for (int e = 0; e < 32; ++e) wv[e] = __builtin_nontemporal_load(wp + (size_t)(k + e) * 12288);
; #pragma unroll
;     for (int e = 0; e < 32; ++e) { a0 += sc[kq * 512 + k + e] * wv[e]; a1 += sx[kq * 512 + k + e] * wv[e]; }
;   }
.Lada_loop:
	s_waitcnt lgkmcnt(0)
	ds_read_b128 v[130:133], v45 offset:64
	ds_read_b128 v[134:137], v45 offset:80
	ds_read_b128 v[138:141], v45 offset:96
	ds_read_b128 v[142:145], v45 offset:112
	ds_read_b128 v[210:213], v45 offset:8256
	ds_read_b128 v[214:217], v45 offset:8272
	ds_read_b128 v[218:221], v45 offset:8288
	ds_read_b128 v[222:225], v45 offset:8304
	s_waitcnt vmcnt(47)
	v_fmac_f32_e32 v48, v66, v114
	v_fmac_f32_e32 v49, v66, v194
	s_add_u32 s0, s0, 0xc000
	s_addc_u32 s1, s1, 0
	global_load_dword v66, v162, s[0:1] nt
	s_waitcnt vmcnt(47)
	v_fmac_f32_e32 v48, v67, v115
	v_fmac_f32_e32 v49, v67, v195
	s_add_u32 s0, s0, 0xc000
	s_addc_u32 s1, s1, 0
	global_load_dword v67, v162, s[0:1] nt
	s_waitcnt vmcnt(47)
	v_fmac_f32_e32 v48, v68, v116
	v_fmac_f32_e32 v49, v68, v196
	s_add_u32 s0, s0, 0xc000
	s_addc_u32 s1, s1, 0
	global_load_dword v68, v162, s[0:1] nt
	s_waitcnt vmcnt(47)
	v_fmac_f32_e32 v48, v69, v117
	v_fmac_f32_e32 v49, v69, v197
	s_add_u32 s0, s0, 0xc000
	s_addc_u32 s1, s1, 0
	global_load_dword v69, v162, s[0:1] nt
	s_waitcnt vmcnt(47)
	v_fmac_f32_e32 v48, v70, v118
	v_fmac_f32_e32 v49, v70, v198
	s_add_u32 s0, s0, 0xc000
	s_addc_u32 s1, s1, 0
	global_load_dword v70, v162, s[0:1] nt
	s_waitcnt vmcnt(47)
	v_fmac_f32_e32 v48, v71, v119
	v_fmac_f32_e32 v49, v71, v199
	s_add_u32 s0, s0, 0xc000
	s_addc_u32 s1, s1, 0
	global_load_dword v71, v162, s[0:1] nt
	s_waitcnt vmcnt(47)
	v_fmac_f32_e32 v48, v72, v120
	v_fmac_f32_e32 v49, v72, v200
	s_add_u32 s0, s0, 0xc000
	s_addc_u32 s1, s1, 0
	global_load_dword v72, v162, s[0:1] nt
	s_waitcnt vmcnt(47)
	v_fmac_f32_e32 v48, v73, v121
	v_fmac_f32_e32 v49, v73, v201
	s_add_u32 s0, s0, 0xc000
	s_addc_u32 s1, s1, 0
	global_load_dword v73, v162, s[0:1] nt
	s_waitcnt vmcnt(47)
	v_fmac_f32_e32 v48, v74, v122
	v_fmac_f32_e32 v49, v74, v202
	s_add_u32 s0, s0, 0xc000
	s_addc_u32 s1, s1, 0
	global_load_dword v74, v162, s[0:1] nt
	s_waitcnt vmcnt(47)
	v_fmac_f32_e32 v48, v75, v123
	v_fmac_f32_e32 v49, v75, v203
	s_add_u32 s0, s0, 0xc000
	s_addc_u32 s1, s1, 0
	global_load_dword v75, v162, s[0:1] nt
	s_waitcnt vmcnt(47)
	v_fmac_f32_e32 v48, v76, v124
	v_fmac_f32_e32 v49, v76, v204
	s_add_u32 s0, s0, 0xc000
	s_addc_u32 s1, s1, 0
	global_load_dword v76, v162, s[0:1] nt
	s_waitcnt vmcnt(47)
	v_fmac_f32_e32 v48, v77, v125
	v_fmac_f32_e32 v49, v77, v205
	s_add_u32 s0, s0, 0xc000
	s_addc_u32 s1, s1, 0
	global_load_dword v77, v162, s[0:1] nt
	s_waitcnt vmcnt(47)
	v_fmac_f32_e32 v48, v78, v126
	v_fmac_f32_e32 v49, v78, v206
	s_add_u32 s0, s0, 0xc000
	s_addc_u32 s1, s1, 0
	global_load_dword v78, v162, s[0:1] nt
	s_waitcnt vmcnt(47)
	v_fmac_f32_e32 v48, v79, v127
	v_fmac_f32_e32 v49, v79, v207
	s_add_u32 s0, s0, 0xc000
	s_addc_u32 s1, s1, 0
	global_load_dword v79, v162, s[0:1] nt
	s_waitcnt vmcnt(47)
	v_fmac_f32_e32 v48, v80, v128
	v_fmac_f32_e32 v49, v80, v208
	s_add_u32 s0, s0, 0xc000
	s_addc_u32 s1, s1, 0
	global_load_dword v80, v162, s[0:1] nt
	s_waitcnt vmcnt(47)
	v_fmac_f32_e32 v48, v81, v129
	v_fmac_f32_e32 v49, v81, v209
	s_add_u32 s0, s0, 0xc000
	s_addc_u32 s1, s1, 0
	global_load_dword v81, v162, s[0:1] nt
	s_waitcnt lgkmcnt(0)
	ds_read_b128 v[146:149], v45 offset:128
	ds_read_b128 v[150:153], v45 offset:144
	ds_read_b128 v[154:157], v45 offset:160
	ds_read_b128 v[158:161], v45 offset:176
	ds_read_b128 v[8:11], v45 offset:8320
	ds_read_b128 v[12:15], v45 offset:8336
	ds_read_b128 v[16:19], v45 offset:8352
	ds_read_b128 v[20:23], v45 offset:8368
	s_waitcnt vmcnt(47)
	v_fmac_f32_e32 v48, v82, v130
	v_fmac_f32_e32 v49, v82, v210
	s_add_u32 s0, s0, 0xc000
	s_addc_u32 s1, s1, 0
	global_load_dword v82, v162, s[0:1] nt
	s_waitcnt vmcnt(47)
	v_fmac_f32_e32 v48, v83, v131
	v_fmac_f32_e32 v49, v83, v211
	s_add_u32 s0, s0, 0xc000
	s_addc_u32 s1, s1, 0
	global_load_dword v83, v162, s[0:1] nt
	s_waitcnt vmcnt(47)
	v_fmac_f32_e32 v48, v84, v132
	v_fmac_f32_e32 v49, v84, v212
	s_add_u32 s0, s0, 0xc000
	s_addc_u32 s1, s1, 0
	global_load_dword v84, v162, s[0:1] nt
	s_waitcnt vmcnt(47)
	v_fmac_f32_e32 v48, v85, v133
	v_fmac_f32_e32 v49, v85, v213
	s_add_u32 s0, s0, 0xc000
	s_addc_u32 s1, s1, 0
	global_load_dword v85, v162, s[0:1] nt
	s_waitcnt vmcnt(47)
	v_fmac_f32_e32 v48, v86, v134
	v_fmac_f32_e32 v49, v86, v214
	s_add_u32 s0, s0, 0xc000
	s_addc_u32 s1, s1, 0
	global_load_dword v86, v162, s[0:1] nt
	s_waitcnt vmcnt(47)
	v_fmac_f32_e32 v48, v87, v135
	v_fmac_f32_e32 v49, v87, v215
	s_add_u32 s0, s0, 0xc000
	s_addc_u32 s1, s1, 0
	global_load_dword v87, v162, s[0:1] nt
	s_waitcnt vmcnt(47)
	v_fmac_f32_e32 v48, v88, v136
	v_fmac_f32_e32 v49, v88, v216
	s_add_u32 s0, s0, 0xc000
	s_addc_u32 s1, s1, 0
	global_load_dword v88, v162, s[0:1] nt
	s_waitcnt vmcnt(47)
	v_fmac_f32_e32 v48, v89, v137
	v_fmac_f32_e32 v49, v89, v217
	s_add_u32 s0, s0, 0xc000
	s_addc_u32 s1, s1, 0
	global_load_dword v89, v162, s[0:1] nt
	s_waitcnt vmcnt(47)
	v_fmac_f32_e32 v48, v90, v138
	v_fmac_f32_e32 v49, v90, v218
	s_add_u32 s0, s0, 0xc000
	s_addc_u32 s1, s1, 0
	global_load_dword v90, v162, s[0:1] nt
	s_waitcnt vmcnt(47)
	v_fmac_f32_e32 v48, v91, v139
	v_fmac_f32_e32 v49, v91, v219
	s_add_u32 s0, s0, 0xc000
	s_addc_u32 s1, s1, 0
	global_load_dword v91, v162, s[0:1] nt
	s_waitcnt vmcnt(47)
	v_fmac_f32_e32 v48, v92, v140
	v_fmac_f32_e32 v49, v92, v220
	s_add_u32 s0, s0, 0xc000
	s_addc_u32 s1, s1, 0
	global_load_dword v92, v162, s[0:1] nt
	s_waitcnt vmcnt(47)
	v_fmac_f32_e32 v48, v93, v141
	v_fmac_f32_e32 v49, v93, v221
	s_add_u32 s0, s0, 0xc000
	s_addc_u32 s1, s1, 0
	global_load_dword v93, v162, s[0:1] nt
	s_waitcnt vmcnt(47)
	v_fmac_f32_e32 v48, v94, v142
	v_fmac_f32_e32 v49, v94, v222
	s_add_u32 s0, s0, 0xc000
	s_addc_u32 s1, s1, 0
	global_load_dword v94, v162, s[0:1] nt
	s_waitcnt vmcnt(47)
; DI void adaln_item(const Params& p, int it, char* smem) {
;     ...
;   for (int k = 0; k < 512; k += 32) {
;     float wv[32];
; #pragma unroll
;     for (int e = 0; e < 32; ++e) wv[e] = __builtin_nontemporal_load(wp + (size_t)(k + e) * 12288);
; #pragma unroll
;     for (int e = 0; e < 32; ++e) { a0 += sc[kq * 512 + k + e] * wv[e]; a1 += sx[kq * 512 + k + e] * wv[e]; }
;   }
	v_fmac_f32_e32 v48, v95, v143
	v_fmac_f32_e32 v49, v95, v223
	s_add_u32 s0, s0, 0xc000
	s_addc_u32 s1, s1, 0
	global_load_dword v95, v162, s[0:1] nt
	s_waitcnt vmcnt(47)
	v_fmac_f32_e32 v48, v96, v144
	v_fmac_f32_e32 v49, v96, v224
	s_add_u32 s0, s0, 0xc000
	s_addc_u32 s1, s1, 0
	global_load_dword v96, v162, s[0:1] nt
	s_waitcnt vmcnt(47)
	v_fmac_f32_e32 v48, v97, v145
	v_fmac_f32_e32 v49, v97, v225
	s_add_u32 s0, s0, 0xc000
	s_addc_u32 s1, s1, 0
	global_load_dword v97, v162, s[0:1] nt
	s_waitcnt lgkmcnt(0)
	ds_read_b128 v[114:117], v45 offset:192
	ds_read_b128 v[118:121], v45 offset:208
	ds_read_b128 v[122:125], v45 offset:224
	ds_read_b128 v[126:129], v45 offset:240
	ds_read_b128 v[194:197], v45 offset:8384
	ds_read_b128 v[198:201], v45 offset:8400
	ds_read_b128 v[202:205], v45 offset:8416
	ds_read_b128 v[206:209], v45 offset:8432
	s_waitcnt vmcnt(47)
	v_fmac_f32_e32 v48, v98, v146
	v_fmac_f32_e32 v49, v98, v8
	s_add_u32 s0, s0, 0xc000
	s_addc_u32 s1, s1, 0
	global_load_dword v98, v162, s[0:1] nt
	s_waitcnt vmcnt(47)
	v_fmac_f32_e32 v48, v99, v147
	v_fmac_f32_e32 v49, v99, v9
	s_add_u32 s0, s0, 0xc000
	s_addc_u32 s1, s1, 0
	global_load_dword v99, v162, s[0:1] nt
	s_waitcnt vmcnt(47)
	v_fmac_f32_e32 v48, v100, v148
	v_fmac_f32_e32 v49, v100, v10
	s_add_u32 s0, s0, 0xc000
	s_addc_u32 s1, s1, 0
	global_load_dword v100, v162, s[0:1] nt
	s_waitcnt vmcnt(47)
	v_fmac_f32_e32 v48, v101, v149
	v_fmac_f32_e32 v49, v101, v11
	s_add_u32 s0, s0, 0xc000
	s_addc_u32 s1, s1, 0
	global_load_dword v101, v162, s[0:1] nt
	s_waitcnt vmcnt(47)
	v_fmac_f32_e32 v48, v102, v150
	v_fmac_f32_e32 v49, v102, v12
	s_add_u32 s0, s0, 0xc000
	s_addc_u32 s1, s1, 0
	global_load_dword v102, v162, s[0:1] nt
	s_waitcnt vmcnt(47)
	v_fmac_f32_e32 v48, v103, v151
	v_fmac_f32_e32 v49, v103, v13
	s_add_u32 s0, s0, 0xc000
	s_addc_u32 s1, s1, 0
	global_load_dword v103, v162, s[0:1] nt
	s_waitcnt vmcnt(47)
	v_fmac_f32_e32 v48, v104, v152
	v_fmac_f32_e32 v49, v104, v14
	s_add_u32 s0, s0, 0xc000
	s_addc_u32 s1, s1, 0
	global_load_dword v104, v162, s[0:1] nt
	s_waitcnt vmcnt(47)
	v_fmac_f32_e32 v48, v105, v153
	v_fmac_f32_e32 v49, v105, v15
	s_add_u32 s0, s0, 0xc000
	s_addc_u32 s1, s1, 0
	global_load_dword v105, v162, s[0:1] nt
	s_waitcnt vmcnt(47)
	v_fmac_f32_e32 v48, v106, v154
	v_fmac_f32_e32 v49, v106, v16
	s_add_u32 s0, s0, 0xc000
	s_addc_u32 s1, s1, 0
	global_load_dword v106, v162, s[0:1] nt
	s_waitcnt vmcnt(47)
	v_fmac_f32_e32 v48, v107, v155
	v_fmac_f32_e32 v49, v107, v17
	s_add_u32 s0, s0, 0xc000
	s_addc_u32 s1, s1, 0
	global_load_dword v107, v162, s[0:1] nt
	s_waitcnt vmcnt(47)
	v_fmac_f32_e32 v48, v108, v156
	v_fmac_f32_e32 v49, v108, v18
	s_add_u32 s0, s0, 0xc000
	s_addc_u32 s1, s1, 0
	global_load_dword v108, v162, s[0:1] nt
	s_waitcnt vmcnt(47)
	v_fmac_f32_e32 v48, v109, v157
	v_fmac_f32_e32 v49, v109, v19
	s_add_u32 s0, s0, 0xc000
	s_addc_u32 s1, s1, 0
	global_load_dword v109, v162, s[0:1] nt
	s_waitcnt vmcnt(47)
	v_fmac_f32_e32 v48, v110, v158
	v_fmac_f32_e32 v49, v110, v20
	s_add_u32 s0, s0, 0xc000
	s_addc_u32 s1, s1, 0
	global_load_dword v110, v162, s[0:1] nt
	s_waitcnt vmcnt(47)
	v_fmac_f32_e32 v48, v111, v159
	v_fmac_f32_e32 v49, v111, v21
	s_add_u32 s0, s0, 0xc000
	s_addc_u32 s1, s1, 0
	global_load_dword v111, v162, s[0:1] nt
	s_waitcnt vmcnt(47)
	v_fmac_f32_e32 v48, v112, v160
	v_fmac_f32_e32 v49, v112, v22
	s_add_u32 s0, s0, 0xc000
	s_addc_u32 s1, s1, 0
	global_load_dword v112, v162, s[0:1] nt
	s_waitcnt vmcnt(47)
	v_fmac_f32_e32 v48, v113, v161
	v_fmac_f32_e32 v49, v113, v23
	s_add_u32 s0, s0, 0xc000
	s_addc_u32 s1, s1, 0
	global_load_dword v113, v162, s[0:1] nt
	v_add_u32_e32 v45, 0xc0, v45
	s_add_i32 s7, s7, 1
	s_cmp_lt_u32 s7, 9
	s_cbranch_scc1 .Lada_loop
	s_waitcnt lgkmcnt(0)
	ds_read_b128 v[130:133], v45 offset:64
	ds_read_b128 v[134:137], v45 offset:80
	ds_read_b128 v[138:141], v45 offset:96
	ds_read_b128 v[142:145], v45 offset:112
	ds_read_b128 v[210:213], v45 offset:8256
	ds_read_b128 v[214:217], v45 offset:8272
	ds_read_b128 v[218:221], v45 offset:8288
	ds_read_b128 v[222:225], v45 offset:8304
	s_waitcnt vmcnt(47)
	v_fmac_f32_e32 v48, v66, v114
	v_fmac_f32_e32 v49, v66, v194
	s_add_u32 s0, s0, 0xc000
	s_addc_u32 s1, s1, 0
	global_load_dword v66, v162, s[0:1] nt
	s_waitcnt vmcnt(47)
	v_fmac_f32_e32 v48, v67, v115
	v_fmac_f32_e32 v49, v67, v195
	s_add_u32 s0, s0, 0xc000
	s_addc_u32 s1, s1, 0
	global_load_dword v67, v162, s[0:1] nt
	s_waitcnt vmcnt(47)
	v_fmac_f32_e32 v48, v68, v116
	v_fmac_f32_e32 v49, v68, v196
	s_add_u32 s0, s0, 0xc000
	s_addc_u32 s1, s1, 0
	global_load_dword v68, v162, s[0:1] nt
	s_waitcnt vmcnt(47)
	v_fmac_f32_e32 v48, v69, v117
	v_fmac_f32_e32 v49, v69, v197
	s_add_u32 s0, s0, 0xc000
	s_addc_u32 s1, s1, 0
	global_load_dword v69, v162, s[0:1] nt
	s_waitcnt vmcnt(47)
	v_fmac_f32_e32 v48, v70, v118
	v_fmac_f32_e32 v49, v70, v198
	s_add_u32 s0, s0, 0xc000
	s_addc_u32 s1, s1, 0
	global_load_dword v70, v162, s[0:1] nt
	s_waitcnt vmcnt(47)
	v_fmac_f32_e32 v48, v71, v119
	v_fmac_f32_e32 v49, v71, v199
	s_add_u32 s0, s0, 0xc000
	s_addc_u32 s1, s1, 0
	global_load_dword v71, v162, s[0:1] nt
	s_waitcnt vmcnt(47)
	v_fmac_f32_e32 v48, v72, v120
	v_fmac_f32_e32 v49, v72, v200
	s_add_u32 s0, s0, 0xc000
	s_addc_u32 s1, s1, 0
	global_load_dword v72, v162, s[0:1] nt
	s_waitcnt vmcnt(47)
	v_fmac_f32_e32 v48, v73, v121
	v_fmac_f32_e32 v49, v73, v201
	s_add_u32 s0, s0, 0xc000
	s_addc_u32 s1, s1, 0
	global_load_dword v73, v162, s[0:1] nt
	s_waitcnt vmcnt(47)
	v_fmac_f32_e32 v48, v74, v122
	v_fmac_f32_e32 v49, v74, v202
	s_add_u32 s0, s0, 0xc000
	s_addc_u32 s1, s1, 0
	global_load_dword v74, v162, s[0:1] nt
	s_waitcnt vmcnt(47)
; DI void adaln_item(const Params& p, int it, char* smem) {
;     ...
;   for (int k = 0; k < 512; k += 32) {
;     float wv[32];
; #pragma unroll
;     for (int e = 0; e < 32; ++e) wv[e] = __builtin_nontemporal_load(wp + (size_t)(k + e) * 12288);
; #pragma unroll
;     for (int e = 0; e < 32; ++e) { a0 += sc[kq * 512 + k + e] * wv[e]; a1 += sx[kq * 512 + k + e] * wv[e]; }
;   }
	v_fmac_f32_e32 v48, v75, v123
	v_fmac_f32_e32 v49, v75, v203
	s_add_u32 s0, s0, 0xc000
	s_addc_u32 s1, s1, 0
	global_load_dword v75, v162, s[0:1] nt
	s_waitcnt vmcnt(47)
	v_fmac_f32_e32 v48, v76, v124
	v_fmac_f32_e32 v49, v76, v204
	s_add_u32 s0, s0, 0xc000
	s_addc_u32 s1, s1, 0
	global_load_dword v76, v162, s[0:1] nt
	s_waitcnt vmcnt(47)
	v_fmac_f32_e32 v48, v77, v125
	v_fmac_f32_e32 v49, v77, v205
	s_add_u32 s0, s0, 0xc000
	s_addc_u32 s1, s1, 0
	global_load_dword v77, v162, s[0:1] nt
	s_waitcnt vmcnt(47)
	v_fmac_f32_e32 v48, v78, v126
	v_fmac_f32_e32 v49, v78, v206
	s_add_u32 s0, s0, 0xc000
	s_addc_u32 s1, s1, 0
	global_load_dword v78, v162, s[0:1] nt
	s_waitcnt vmcnt(47)
	v_fmac_f32_e32 v48, v79, v127
	v_fmac_f32_e32 v49, v79, v207
	s_add_u32 s0, s0, 0xc000
	s_addc_u32 s1, s1, 0
	global_load_dword v79, v162, s[0:1] nt
	s_waitcnt vmcnt(47)
	v_fmac_f32_e32 v48, v80, v128
	v_fmac_f32_e32 v49, v80, v208
	s_add_u32 s0, s0, 0xc000
	s_addc_u32 s1, s1, 0
	global_load_dword v80, v162, s[0:1] nt
	s_waitcnt vmcnt(47)
	v_fmac_f32_e32 v48, v81, v129
	v_fmac_f32_e32 v49, v81, v209
	s_add_u32 s0, s0, 0xc000
	s_addc_u32 s1, s1, 0
	global_load_dword v81, v162, s[0:1] nt
	s_waitcnt lgkmcnt(0)
	ds_read_b128 v[146:149], v45 offset:128
	ds_read_b128 v[150:153], v45 offset:144
	ds_read_b128 v[154:157], v45 offset:160
	ds_read_b128 v[158:161], v45 offset:176
	ds_read_b128 v[8:11], v45 offset:8320
	ds_read_b128 v[12:15], v45 offset:8336
	ds_read_b128 v[16:19], v45 offset:8352
	ds_read_b128 v[20:23], v45 offset:8368
	s_waitcnt vmcnt(47)
	v_fmac_f32_e32 v48, v82, v130
	v_fmac_f32_e32 v49, v82, v210
	s_add_u32 s0, s0, 0xc000
	s_addc_u32 s1, s1, 0
	global_load_dword v82, v162, s[0:1] nt
	s_waitcnt vmcnt(47)
	v_fmac_f32_e32 v48, v83, v131
	v_fmac_f32_e32 v49, v83, v211
	s_add_u32 s0, s0, 0xc000
	s_addc_u32 s1, s1, 0
	global_load_dword v83, v162, s[0:1] nt
	s_waitcnt vmcnt(47)
	v_fmac_f32_e32 v48, v84, v132
	v_fmac_f32_e32 v49, v84, v212
	s_add_u32 s0, s0, 0xc000
	s_addc_u32 s1, s1, 0
	global_load_dword v84, v162, s[0:1] nt
	s_waitcnt vmcnt(47)
	v_fmac_f32_e32 v48, v85, v133
	v_fmac_f32_e32 v49, v85, v213
	s_add_u32 s0, s0, 0xc000
	s_addc_u32 s1, s1, 0
	global_load_dword v85, v162, s[0:1] nt
	s_waitcnt vmcnt(47)
	v_fmac_f32_e32 v48, v86, v134
	v_fmac_f32_e32 v49, v86, v214
	s_add_u32 s0, s0, 0xc000
	s_addc_u32 s1, s1, 0
	global_load_dword v86, v162, s[0:1] nt
	s_waitcnt vmcnt(47)
	v_fmac_f32_e32 v48, v87, v135
	v_fmac_f32_e32 v49, v87, v215
	s_add_u32 s0, s0, 0xc000
	s_addc_u32 s1, s1, 0
	global_load_dword v87, v162, s[0:1] nt
	s_waitcnt vmcnt(47)
	v_fmac_f32_e32 v48, v88, v136
	v_fmac_f32_e32 v49, v88, v216
	s_add_u32 s0, s0, 0xc000
	s_addc_u32 s1, s1, 0
	global_load_dword v88, v162, s[0:1] nt
	s_waitcnt vmcnt(47)
	v_fmac_f32_e32 v48, v89, v137
	v_fmac_f32_e32 v49, v89, v217
	s_add_u32 s0, s0, 0xc000
	s_addc_u32 s1, s1, 0
	global_load_dword v89, v162, s[0:1] nt
	s_waitcnt vmcnt(47)
	v_fmac_f32_e32 v48, v90, v138
	v_fmac_f32_e32 v49, v90, v218
	s_add_u32 s0, s0, 0xc000
	s_addc_u32 s1, s1, 0
	global_load_dword v90, v162, s[0:1] nt
	s_waitcnt vmcnt(47)
	v_fmac_f32_e32 v48, v91, v139
	v_fmac_f32_e32 v49, v91, v219
	s_add_u32 s0, s0, 0xc000
	s_addc_u32 s1, s1, 0
	global_load_dword v91, v162, s[0:1] nt
	s_waitcnt vmcnt(47)
	v_fmac_f32_e32 v48, v92, v140
	v_fmac_f32_e32 v49, v92, v220
	s_add_u32 s0, s0, 0xc000
	s_addc_u32 s1, s1, 0
	global_load_dword v92, v162, s[0:1] nt
	s_waitcnt vmcnt(47)
	v_fmac_f32_e32 v48, v93, v141
	v_fmac_f32_e32 v49, v93, v221
	s_add_u32 s0, s0, 0xc000
	s_addc_u32 s1, s1, 0
	global_load_dword v93, v162, s[0:1] nt
	s_waitcnt vmcnt(47)
	v_fmac_f32_e32 v48, v94, v142
	v_fmac_f32_e32 v49, v94, v222
	s_add_u32 s0, s0, 0xc000
	s_addc_u32 s1, s1, 0
	global_load_dword v94, v162, s[0:1] nt
	s_waitcnt vmcnt(47)
	v_fmac_f32_e32 v48, v95, v143
	v_fmac_f32_e32 v49, v95, v223
	s_add_u32 s0, s0, 0xc000
	s_addc_u32 s1, s1, 0
	global_load_dword v95, v162, s[0:1] nt
	s_waitcnt vmcnt(47)
	v_fmac_f32_e32 v48, v96, v144
	v_fmac_f32_e32 v49, v96, v224
	s_add_u32 s0, s0, 0xc000
	s_addc_u32 s1, s1, 0
	global_load_dword v96, v162, s[0:1] nt
	s_waitcnt vmcnt(47)
	v_fmac_f32_e32 v48, v97, v145
	v_fmac_f32_e32 v49, v97, v225
	s_add_u32 s0, s0, 0xc000
	s_addc_u32 s1, s1, 0
	global_load_dword v97, v162, s[0:1] nt
	s_waitcnt lgkmcnt(0)
	ds_read_b128 v[114:117], v45 offset:192
	ds_read_b128 v[118:121], v45 offset:208
	ds_read_b128 v[122:125], v45 offset:224
	ds_read_b128 v[126:129], v45 offset:240
	ds_read_b128 v[194:197], v45 offset:8384
	ds_read_b128 v[198:201], v45 offset:8400
	ds_read_b128 v[202:205], v45 offset:8416
	ds_read_b128 v[206:209], v45 offset:8432
	s_waitcnt vmcnt(47)
	v_fmac_f32_e32 v48, v98, v146
	v_fmac_f32_e32 v49, v98, v8
	s_waitcnt vmcnt(46)
	v_fmac_f32_e32 v48, v99, v147
	v_fmac_f32_e32 v49, v99, v9
	s_waitcnt vmcnt(45)
	v_fmac_f32_e32 v48, v100, v148
	v_fmac_f32_e32 v49, v100, v10
	s_waitcnt vmcnt(44)
	v_fmac_f32_e32 v48, v101, v149
	v_fmac_f32_e32 v49, v101, v11
	s_waitcnt vmcnt(43)
	v_fmac_f32_e32 v48, v102, v150
	v_fmac_f32_e32 v49, v102, v12
	s_waitcnt vmcnt(42)
; DI void adaln_item(const Params& p, int it, char* smem) {
;     ...
;   for (int k = 0; k < 512; k += 32) {
;     float wv[32];
; #pragma unroll
;     for (int e = 0; e < 32; ++e) wv[e] = __builtin_nontemporal_load(wp + (size_t)(k + e) * 12288);
; #pragma unroll
;     for (int e = 0; e < 32; ++e) { a0 += sc[kq * 512 + k + e] * wv[e]; a1 += sx[kq * 512 + k + e] * wv[e]; }
;   }
;   red[(kq * 64 + col) * 2] = a0; red[(kq * 64 + col) * 2 + 1] = a1;
;   __syncthreads();
;   if (t < 128) {
;     const int cc = t & 63, s = t >> 6;
;     float sum = 0.f;
; #pragma unroll
;     for (int q = 0; q < 4; ++q) sum += red[(q * 64 + cc) * 2 + s];
;     float* mods = (float*)(p.ws + O_MODS);
;     mods[(size_t)(l * 2 + s) * 12288 + n0 + cc] = sum + p.b_ada[l * 12288 + n0 + cc];
;   }
	v_fmac_f32_e32 v48, v103, v151
	v_fmac_f32_e32 v49, v103, v13
	s_waitcnt vmcnt(41)
	v_fmac_f32_e32 v48, v104, v152
	v_fmac_f32_e32 v49, v104, v14
	s_waitcnt vmcnt(40)
	v_fmac_f32_e32 v48, v105, v153
	v_fmac_f32_e32 v49, v105, v15
	s_waitcnt vmcnt(39)
	v_fmac_f32_e32 v48, v106, v154
	v_fmac_f32_e32 v49, v106, v16
	s_waitcnt vmcnt(38)
	v_fmac_f32_e32 v48, v107, v155
	v_fmac_f32_e32 v49, v107, v17
	s_waitcnt vmcnt(37)
	v_fmac_f32_e32 v48, v108, v156
	v_fmac_f32_e32 v49, v108, v18
	s_waitcnt vmcnt(36)
	v_fmac_f32_e32 v48, v109, v157
	v_fmac_f32_e32 v49, v109, v19
	s_waitcnt vmcnt(35)
	v_fmac_f32_e32 v48, v110, v158
	v_fmac_f32_e32 v49, v110, v20
	s_waitcnt vmcnt(34)
	v_fmac_f32_e32 v48, v111, v159
	v_fmac_f32_e32 v49, v111, v21
	s_waitcnt vmcnt(33)
	v_fmac_f32_e32 v48, v112, v160
	v_fmac_f32_e32 v49, v112, v22
	s_waitcnt vmcnt(32)
	v_fmac_f32_e32 v48, v113, v161
	v_fmac_f32_e32 v49, v113, v23
	s_waitcnt lgkmcnt(0)
	ds_read_b128 v[130:133], v45 offset:256
	ds_read_b128 v[134:137], v45 offset:272
	ds_read_b128 v[138:141], v45 offset:288
	ds_read_b128 v[142:145], v45 offset:304
	ds_read_b128 v[210:213], v45 offset:8448
	ds_read_b128 v[214:217], v45 offset:8464
	ds_read_b128 v[218:221], v45 offset:8480
	ds_read_b128 v[222:225], v45 offset:8496
	s_waitcnt vmcnt(31)
	v_fmac_f32_e32 v48, v66, v114
	v_fmac_f32_e32 v49, v66, v194
	s_waitcnt vmcnt(30)
	v_fmac_f32_e32 v48, v67, v115
	v_fmac_f32_e32 v49, v67, v195
	s_waitcnt vmcnt(29)
	v_fmac_f32_e32 v48, v68, v116
	v_fmac_f32_e32 v49, v68, v196
	s_waitcnt vmcnt(28)
	v_fmac_f32_e32 v48, v69, v117
	v_fmac_f32_e32 v49, v69, v197
	s_waitcnt vmcnt(27)
	v_fmac_f32_e32 v48, v70, v118
	v_fmac_f32_e32 v49, v70, v198
	s_waitcnt vmcnt(26)
	v_fmac_f32_e32 v48, v71, v119
	v_fmac_f32_e32 v49, v71, v199
	s_waitcnt vmcnt(25)
	v_fmac_f32_e32 v48, v72, v120
	v_fmac_f32_e32 v49, v72, v200
	s_waitcnt vmcnt(24)
	v_fmac_f32_e32 v48, v73, v121
	v_fmac_f32_e32 v49, v73, v201
	s_waitcnt vmcnt(23)
	v_fmac_f32_e32 v48, v74, v122
	v_fmac_f32_e32 v49, v74, v202
	s_waitcnt vmcnt(22)
	v_fmac_f32_e32 v48, v75, v123
	v_fmac_f32_e32 v49, v75, v203
	s_waitcnt vmcnt(21)
	v_fmac_f32_e32 v48, v76, v124
	v_fmac_f32_e32 v49, v76, v204
	s_waitcnt vmcnt(20)
	v_fmac_f32_e32 v48, v77, v125
	v_fmac_f32_e32 v49, v77, v205
	s_waitcnt vmcnt(19)
	v_fmac_f32_e32 v48, v78, v126
	v_fmac_f32_e32 v49, v78, v206
	s_waitcnt vmcnt(18)
	v_fmac_f32_e32 v48, v79, v127
	v_fmac_f32_e32 v49, v79, v207
	s_waitcnt vmcnt(17)
	v_fmac_f32_e32 v48, v80, v128
	v_fmac_f32_e32 v49, v80, v208
	s_waitcnt vmcnt(16)
	v_fmac_f32_e32 v48, v81, v129
	v_fmac_f32_e32 v49, v81, v209
	s_waitcnt lgkmcnt(0)
	s_waitcnt vmcnt(15)
	v_fmac_f32_e32 v48, v82, v130
	v_fmac_f32_e32 v49, v82, v210
	s_waitcnt vmcnt(14)
	v_fmac_f32_e32 v48, v83, v131
	v_fmac_f32_e32 v49, v83, v211
	s_waitcnt vmcnt(13)
	v_fmac_f32_e32 v48, v84, v132
	v_fmac_f32_e32 v49, v84, v212
	s_waitcnt vmcnt(12)
	v_fmac_f32_e32 v48, v85, v133
	v_fmac_f32_e32 v49, v85, v213
	s_waitcnt vmcnt(11)
	v_fmac_f32_e32 v48, v86, v134
	v_fmac_f32_e32 v49, v86, v214
	s_waitcnt vmcnt(10)
	v_fmac_f32_e32 v48, v87, v135
	v_fmac_f32_e32 v49, v87, v215
	s_waitcnt vmcnt(9)
	v_fmac_f32_e32 v48, v88, v136
	v_fmac_f32_e32 v49, v88, v216
	s_waitcnt vmcnt(8)
	v_fmac_f32_e32 v48, v89, v137
	v_fmac_f32_e32 v49, v89, v217
	s_waitcnt vmcnt(7)
	v_fmac_f32_e32 v48, v90, v138
	v_fmac_f32_e32 v49, v90, v218
	s_waitcnt vmcnt(6)
	v_fmac_f32_e32 v48, v91, v139
	v_fmac_f32_e32 v49, v91, v219
	s_waitcnt vmcnt(5)
	v_fmac_f32_e32 v48, v92, v140
	v_fmac_f32_e32 v49, v92, v220
	s_waitcnt vmcnt(4)
	v_fmac_f32_e32 v48, v93, v141
	v_fmac_f32_e32 v49, v93, v221
	s_waitcnt vmcnt(3)
	v_fmac_f32_e32 v48, v94, v142
	v_fmac_f32_e32 v49, v94, v222
	s_waitcnt vmcnt(2)
	v_fmac_f32_e32 v48, v95, v143
	v_fmac_f32_e32 v49, v95, v223
	s_waitcnt vmcnt(1)
	v_fmac_f32_e32 v48, v96, v144
	v_fmac_f32_e32 v49, v96, v224
	s_waitcnt vmcnt(0)
	v_fmac_f32_e32 v48, v97, v145
	v_fmac_f32_e32 v49, v97, v225
	s_movk_i32 s0, 0x80
	v_lshl_add_u32 v2, v42, 3, s3
	v_cmp_gt_i32_e32 vcc, s0, v42
	ds_write_b64 v2, v[48:49] offset:16384
	s_waitcnt lgkmcnt(0)
	s_barrier
	s_and_saveexec_b64 s[0:1], vcc
	v_readlane_b32 s40, v254, 51
	v_readlane_b32 s41, v254, 52
	s_cbranch_execz .LBB0_12
	s_mul_i32 s7, s6, 0x3000
	s_add_i32 s7, s7, s4
	v_or_b32_e32 v2, s7, v44
	v_ashrrev_i32_e32 v3, 31, v2
	v_lshl_add_u64 v[2:3], v[2:3], 2, s[78:79]
	global_load_dword v8, v[2:3], off
	v_lshlrev_b32_e32 v4, 3, v44
	v_lshlrev_b32_e32 v5, 2, v43
	v_add3_u32 v6, s3, v4, v5
	ds_read2st64_b32 v[4:5], v6 offset0:64 offset1:66
	ds_read2st64_b32 v[6:7], v6 offset0:68 offset1:70
	v_lshl_add_u32 v9, s6, 1, v43
	v_mov_b64_e32 v[2:3], s[40:41]
	s_mov_b32 s6, 0xc000
	s_waitcnt lgkmcnt(1)
	v_add_f32_e32 v4, 0, v4
	v_add_f32_e32 v4, v4, v5
	v_mad_i64_i32 v[2:3], s[6:7], v9, s6, v[2:3]
	s_waitcnt lgkmcnt(0)
	v_add_f32_e32 v4, v4, v6
	v_lshlrev_b32_e32 v180, 2, v44
	v_lshl_add_u64 v[2:3], s[4:5], 2, v[2:3]
	v_add_f32_e32 v4, v4, v7
	v_lshl_add_u64 v[2:3], v[2:3], 0, v[180:181]
	s_waitcnt vmcnt(0)
	v_add_f32_e32 v4, v4, v8
	global_store_dword v[2:3], v4, off
	s_branch .LBB0_12
